# neighbourhood attention P.V block: the four wave-uniform skip tests become s_cmp/s_cbranch on per-task SGPR flags instead of readlane/cndmask/cmp ballots between the MFMAs (7.12)
# baseline (speedup 1.0000x reference)
.LBB0_233:
	s_cmp_lt_i32 s7, -11
	s_mov_b32 s78, 0
	s_cbranch_scc1 .LBB0_229
	s_waitcnt lgkmcnt(0)
	v_pk_add_f32 v[0:1], v[0:1], v[2:3]
	v_readlane_b32 s7, v252, 9
	v_mul_f32_e32 v0, v0, v1
	v_mul_f32_e32 v1, 0x4f800000, v0
	v_cmp_gt_f32_e32 vcc, s79, v0
	s_max_u32 s6, s6, 4
	s_min_u32 s7, s9, 56
	v_cndmask_b32_e32 v0, v0, v1, vcc
	v_sqrt_f32_e32 v1, v0
	s_mul_i32 s9, s6, 0x7c
	v_add_u32_e32 v4, s9, v162
	s_mulk_i32 s3, 0x1f0
	v_add_u32_e32 v2, -1, v1
	v_fma_f32 v3, -v2, v1, v0
	v_cmp_ge_f32_e64 s[74:75], 0, v3
	v_add_u32_e32 v3, 1, v1
	v_subrev_u32_e32 v147, s3, v4
	v_cndmask_b32_e64 v2, v1, v2, s[74:75]
	v_fma_f32 v1, -v3, v1, v0
	v_cmp_lt_f32_e64 s[74:75], 0, v1
	s_max_i32 s3, s8, 4
	v_readlane_b32 s8, v255, 34
	v_cndmask_b32_e64 v1, v2, v3, s[74:75]
	v_mul_f32_e32 v2, 0x37800000, v1
	v_cndmask_b32_e32 v1, v1, v2, vcc
	v_cmp_class_f32_e32 vcc, v0, v215
	v_readlane_b32 s9, v255, 35
	v_mov_b32_e32 v16, 0
	v_cndmask_b32_e32 v0, v1, v0, vcc
	v_fmamk_f32 v0, v0, 0x3f8147ae, v139
	v_add_f32_e32 v0, 0x3a83126f, v0
	v_cndmask_b32_e64 v32, v233, -v0, s[8:9]
	v_readlane_b32 s8, v255, 36
	v_readlane_b32 s9, v255, 37
	s_add_i32 s3, s3, -4
	v_mov_b32_e32 v17, v16
	v_cndmask_b32_e64 v48, v233, -v0, s[8:9]
	v_readlane_b32 s8, v255, 38
	v_readlane_b32 s9, v255, 39
	s_min_u32 s81, s3, 56
	v_cndmask_b32_e64 v49, v233, -v0, s[14:15]
	v_cndmask_b32_e64 v33, v233, -v0, s[8:9]
	v_cndmask_b32_e64 v34, v233, -v0, s[16:17]
	v_cndmask_b32_e64 v50, v233, -v0, s[18:19]
	v_cndmask_b32_e64 v35, v233, -v0, s[20:21]
	v_cndmask_b32_e64 v51, v233, -v0, s[22:23]
	v_cndmask_b32_e64 v36, v233, -v0, s[24:25]
	v_cndmask_b32_e64 v52, v233, -v0, s[26:27]
	v_cndmask_b32_e64 v37, v233, -v0, s[28:29]
	v_cndmask_b32_e64 v53, v233, -v0, s[30:31]
	v_cndmask_b32_e64 v38, v233, -v0, s[34:35]
	v_cndmask_b32_e64 v54, v233, -v0, s[36:37]
	v_cndmask_b32_e64 v39, v233, -v0, s[38:39]
	v_cndmask_b32_e64 v55, v233, -v0, s[40:41]
	v_cndmask_b32_e64 v40, v233, -v0, s[42:43]
	v_cndmask_b32_e64 v56, v233, -v0, s[44:45]
	v_cndmask_b32_e64 v41, v233, -v0, s[46:47]
	v_cndmask_b32_e64 v57, v233, -v0, s[48:49]
	v_cndmask_b32_e64 v42, v233, -v0, s[50:51]
	v_cndmask_b32_e64 v58, v233, -v0, s[52:53]
	v_cndmask_b32_e64 v43, v233, -v0, s[54:55]
	v_cndmask_b32_e64 v59, v233, -v0, s[56:57]
	v_cndmask_b32_e64 v44, v233, -v0, s[58:59]
	v_cndmask_b32_e64 v60, v233, -v0, s[60:61]
	v_cndmask_b32_e64 v45, v233, -v0, s[62:63]
	v_cndmask_b32_e64 v61, v233, -v0, s[64:65]
	v_cndmask_b32_e64 v46, v233, -v0, s[66:67]
	v_cndmask_b32_e64 v62, v233, -v0, s[68:69]
	v_cndmask_b32_e64 v47, v233, -v0, s[70:71]
	v_cndmask_b32_e64 v63, v233, -v0, s[72:73]
	v_mov_b32_e32 v18, v16
	v_mov_b32_e32 v19, v16
	v_mov_b32_e32 v20, v16
	v_mov_b32_e32 v21, v16
	v_mov_b32_e32 v22, v16
	v_mov_b32_e32 v23, v16
	v_mov_b32_e32 v24, v16
	v_mov_b32_e32 v25, v16
	v_mov_b32_e32 v26, v16
	v_mov_b32_e32 v27, v16
	v_mov_b32_e32 v28, v16
	v_mov_b32_e32 v29, v16
	v_mov_b32_e32 v30, v16
	v_mov_b32_e32 v31, v16
	v_mov_b64_e32 v[0:1], v[16:17]
	s_mov_b32 s12, s87
	s_sub_i32 s7, s7, s6
	s_add_i32 s3, s81, 7
	s_mov_b32 s87, -12
	s_mov_b32 s8, 5
	v_readlane_b32 s9, v252, 50
	v_mov_b64_e32 v[2:3], v[18:19]
	v_mov_b64_e32 v[4:5], v[20:21]
	v_mov_b64_e32 v[6:7], v[22:23]
	v_mov_b64_e32 v[8:9], v[24:25]
	v_mov_b64_e32 v[10:11], v[26:27]
	v_mov_b64_e32 v[12:13], v[28:29]
	v_mov_b64_e32 v[14:15], v[30:31]
	v_mov_b32_e32 v64, v16
	s_mov_b32 s10, 0
	v_readlane_b32 s100, v252, 30
	v_readlane_b32 s101, v252, 32
	s_nop 3

.LBB0_240:
	v_add3_u32 v66, s11, v155, v156
	v_add_u32_e32 v66, v66, v144
	ds_read_b64_tr_b16 v[174:175], v66 offset:8192
	ds_read_b64_tr_b16 v[176:177], v66 offset:8704
	ds_read_b64_tr_b16 v[178:179], v66 offset:9216
	ds_read_b64_tr_b16 v[180:181], v66 offset:9728
	ds_read_b64_tr_b16 v[182:183], v66 offset:10240
	ds_read_b64_tr_b16 v[184:185], v66 offset:10752
	ds_read_b64_tr_b16 v[186:187], v66 offset:11264
	ds_read_b64_tr_b16 v[188:189], v66 offset:11776
	ds_read_b64_tr_b16 v[190:191], v66 offset:12288
	ds_read_b64_tr_b16 v[192:193], v66 offset:12800
	ds_read_b64_tr_b16 v[194:195], v66 offset:13312
	ds_read_b64_tr_b16 v[196:197], v66 offset:13824
	s_cmp_eq_u32 s100, 0
	s_cbranch_scc1 .LBB0_242
	s_waitcnt lgkmcnt(10)
	v_mfma_f32_32x32x16_bf16 v[16:31], v[174:177], v[114:117], v[16:31]
.LBB0_242:
	s_waitcnt lgkmcnt(8)
	v_mfma_f32_32x32x16_bf16 v[16:31], v[178:181], v[130:133], v[16:31]
	ds_read_b64_tr_b16 v[198:199], v66 offset:14336
	ds_read_b64_tr_b16 v[200:201], v66 offset:14848
	ds_read_b64_tr_b16 v[202:203], v66 offset:15360
	ds_read_b64_tr_b16 v[204:205], v66 offset:15872
	s_waitcnt lgkmcnt(10)
	v_mfma_f32_32x32x16_bf16 v[16:31], v[182:185], v[126:129], v[16:31]
	s_cmp_eq_u32 s101, 0
	s_cbranch_scc1 .LBB0_244
	s_waitcnt lgkmcnt(8)
	v_mfma_f32_32x32x16_bf16 v[16:31], v[186:189], v[134:137], v[16:31]
.LBB0_244:
	s_cmp_eq_u32 s100, 0
	s_cbranch_scc1 .LBB0_246
	s_waitcnt lgkmcnt(6)
	v_mfma_f32_32x32x16_bf16 v[0:15], v[190:193], v[114:117], v[0:15]
.LBB0_246:
	s_waitcnt lgkmcnt(4)
	s_nop 5
	v_mfma_f32_32x32x16_bf16 v[0:15], v[194:197], v[130:133], v[0:15]
	s_waitcnt lgkmcnt(2)
	v_mfma_f32_32x32x16_bf16 v[0:15], v[198:201], v[126:129], v[0:15]
	s_cmp_eq_u32 s101, 0
	s_cbranch_scc1 .LBB0_248
	s_waitcnt lgkmcnt(0)
	v_mfma_f32_32x32x16_bf16 v[0:15], v[202:205], v[134:137], v[0:15]
